# PW L-build loop rewritten by hand: the 20 per-thread P loads of each 10-element pass issued together (one wait) instead of one round trip per element; branch-free select, same arithmetic
# speedup vs baseline: 1.0185x; 1.0029x over previous
.LBB0_537:
	s_mov_b32 s22, 0x66666667
	s_movk_i32 s23, 0x1fff
	s_movk_i32 s24, 0xc00
	s_movk_i32 s25, 0xa0
	v_mov_b64_e32 v[10:11], s[86:87]
	v_mul_hi_i32 v2, v5, s22
	v_lshrrev_b32_e32 v3, 31, v2
	v_ashrrev_i32_e32 v2, 7, v2
	v_add_u32_e32 v6, v2, v3
	v_add_u32_e32 v8, s57, v6
	v_and_b32_e32 v2, 0x7ff, v8
	v_add_u32_e32 v3, -1, v8
	v_cmp_ne_u32_e32 vcc, 0, v2
	v_mul_i32_i24_e32 v7, 0x140, v6
	s_nop 0
	v_cndmask_b32_e32 v9, -1, v3, vcc
	v_add_u32_e32 v3, 8, v8
	v_cmp_lt_i32_e32 vcc, s23, v8
	v_sub_u32_e32 v2, v5, v7
	s_nop 0
	v_cndmask_b32_e32 v9, v9, v3, vcc
	v_ashrrev_i32_e32 v3, 31, v2
	v_cmp_lt_i32_e32 vcc, -1, v9
	v_lshlrev_b64 v[14:15], 2, v[2:3]
	v_mov_b32_e32 v48, v2
	v_cndmask_b32_e32 v3, v8, v9, vcc
	v_mad_i64_i32 v[12:13], s[44:45], v8, s24, v[10:11]
	v_mad_i64_i32 v[8:9], s[44:45], v3, s24, v[10:11]
	v_lshl_add_u64 v[12:13], v[12:13], 0, v[14:15]
	v_lshl_add_u64 v[8:9], v[8:9], 0, v[14:15]
	global_load_dword v18, v[12:13], off
	global_load_dword v28, v[8:9], off offset:1536
	v_cndmask_b32_e64 v38, 0, 1.0, vcc
	v_mov_b32_e32 v58, v6
	v_add_u32_e32 v5, 0x200, v5
	v_mul_hi_i32 v2, v5, s22
	v_lshrrev_b32_e32 v3, 31, v2
	v_ashrrev_i32_e32 v2, 7, v2
	v_add_u32_e32 v6, v2, v3
	v_add_u32_e32 v8, s57, v6
	v_and_b32_e32 v2, 0x7ff, v8
	v_add_u32_e32 v3, -1, v8
	v_cmp_ne_u32_e32 vcc, 0, v2
	v_mul_i32_i24_e32 v7, 0x140, v6
	s_nop 0
	v_cndmask_b32_e32 v9, -1, v3, vcc
	v_add_u32_e32 v3, 8, v8
	v_cmp_lt_i32_e32 vcc, s23, v8
	v_sub_u32_e32 v2, v5, v7
	s_nop 0
	v_cndmask_b32_e32 v9, v9, v3, vcc
	v_ashrrev_i32_e32 v3, 31, v2
	v_cmp_lt_i32_e32 vcc, -1, v9
	v_lshlrev_b64 v[14:15], 2, v[2:3]
	v_mov_b32_e32 v49, v2
	v_cndmask_b32_e32 v3, v8, v9, vcc
	v_mad_i64_i32 v[12:13], s[44:45], v8, s24, v[10:11]
	v_mad_i64_i32 v[8:9], s[44:45], v3, s24, v[10:11]
	v_lshl_add_u64 v[12:13], v[12:13], 0, v[14:15]
	v_lshl_add_u64 v[8:9], v[8:9], 0, v[14:15]
	global_load_dword v19, v[12:13], off
	global_load_dword v29, v[8:9], off offset:1536
	v_cndmask_b32_e64 v39, 0, 1.0, vcc
	v_mov_b32_e32 v59, v6
	v_add_u32_e32 v5, 0x200, v5
	v_mul_hi_i32 v2, v5, s22
	v_lshrrev_b32_e32 v3, 31, v2
	v_ashrrev_i32_e32 v2, 7, v2
	v_add_u32_e32 v6, v2, v3
	v_add_u32_e32 v8, s57, v6
	v_and_b32_e32 v2, 0x7ff, v8
	v_add_u32_e32 v3, -1, v8
	v_cmp_ne_u32_e32 vcc, 0, v2
	v_mul_i32_i24_e32 v7, 0x140, v6
	s_nop 0
	v_cndmask_b32_e32 v9, -1, v3, vcc
	v_add_u32_e32 v3, 8, v8
	v_cmp_lt_i32_e32 vcc, s23, v8
	v_sub_u32_e32 v2, v5, v7
	s_nop 0
	v_cndmask_b32_e32 v9, v9, v3, vcc
	v_ashrrev_i32_e32 v3, 31, v2
	v_cmp_lt_i32_e32 vcc, -1, v9
	v_lshlrev_b64 v[14:15], 2, v[2:3]
	v_mov_b32_e32 v50, v2
	v_cndmask_b32_e32 v3, v8, v9, vcc
	v_mad_i64_i32 v[12:13], s[44:45], v8, s24, v[10:11]
	v_mad_i64_i32 v[8:9], s[44:45], v3, s24, v[10:11]
	v_lshl_add_u64 v[12:13], v[12:13], 0, v[14:15]
	v_lshl_add_u64 v[8:9], v[8:9], 0, v[14:15]
	global_load_dword v20, v[12:13], off
	global_load_dword v30, v[8:9], off offset:1536
	v_cndmask_b32_e64 v40, 0, 1.0, vcc
	v_mov_b32_e32 v60, v6
	v_add_u32_e32 v5, 0x200, v5
	v_mul_hi_i32 v2, v5, s22
	v_lshrrev_b32_e32 v3, 31, v2
	v_ashrrev_i32_e32 v2, 7, v2
	v_add_u32_e32 v6, v2, v3
	v_add_u32_e32 v8, s57, v6
	v_and_b32_e32 v2, 0x7ff, v8
	v_add_u32_e32 v3, -1, v8
	v_cmp_ne_u32_e32 vcc, 0, v2
	v_mul_i32_i24_e32 v7, 0x140, v6
	s_nop 0
	v_cndmask_b32_e32 v9, -1, v3, vcc
	v_add_u32_e32 v3, 8, v8
	v_cmp_lt_i32_e32 vcc, s23, v8
	v_sub_u32_e32 v2, v5, v7
	s_nop 0
	v_cndmask_b32_e32 v9, v9, v3, vcc
	v_ashrrev_i32_e32 v3, 31, v2
	v_cmp_lt_i32_e32 vcc, -1, v9
	v_lshlrev_b64 v[14:15], 2, v[2:3]
	v_mov_b32_e32 v51, v2
	v_cndmask_b32_e32 v3, v8, v9, vcc
	v_mad_i64_i32 v[12:13], s[44:45], v8, s24, v[10:11]
	v_mad_i64_i32 v[8:9], s[44:45], v3, s24, v[10:11]
	v_lshl_add_u64 v[12:13], v[12:13], 0, v[14:15]
	v_lshl_add_u64 v[8:9], v[8:9], 0, v[14:15]
	global_load_dword v21, v[12:13], off
	global_load_dword v31, v[8:9], off offset:1536
	v_cndmask_b32_e64 v41, 0, 1.0, vcc
	v_mov_b32_e32 v61, v6
	v_add_u32_e32 v5, 0x200, v5
	v_mul_hi_i32 v2, v5, s22
	v_lshrrev_b32_e32 v3, 31, v2
	v_ashrrev_i32_e32 v2, 7, v2
	v_add_u32_e32 v6, v2, v3
	v_add_u32_e32 v8, s57, v6
	v_and_b32_e32 v2, 0x7ff, v8
	v_add_u32_e32 v3, -1, v8
	v_cmp_ne_u32_e32 vcc, 0, v2
	v_mul_i32_i24_e32 v7, 0x140, v6
	s_nop 0
	v_cndmask_b32_e32 v9, -1, v3, vcc
	v_add_u32_e32 v3, 8, v8
	v_cmp_lt_i32_e32 vcc, s23, v8
	v_sub_u32_e32 v2, v5, v7
	s_nop 0
	v_cndmask_b32_e32 v9, v9, v3, vcc
	v_ashrrev_i32_e32 v3, 31, v2
	v_cmp_lt_i32_e32 vcc, -1, v9
	v_lshlrev_b64 v[14:15], 2, v[2:3]
	v_mov_b32_e32 v52, v2
	v_cndmask_b32_e32 v3, v8, v9, vcc
	v_mad_i64_i32 v[12:13], s[44:45], v8, s24, v[10:11]
	v_mad_i64_i32 v[8:9], s[44:45], v3, s24, v[10:11]
	v_lshl_add_u64 v[12:13], v[12:13], 0, v[14:15]
	v_lshl_add_u64 v[8:9], v[8:9], 0, v[14:15]
	global_load_dword v22, v[12:13], off
	global_load_dword v32, v[8:9], off offset:1536
	v_cndmask_b32_e64 v42, 0, 1.0, vcc
	v_mov_b32_e32 v62, v6
	v_add_u32_e32 v5, 0x200, v5
	v_mul_hi_i32 v2, v5, s22
	v_lshrrev_b32_e32 v3, 31, v2
	v_ashrrev_i32_e32 v2, 7, v2
	v_add_u32_e32 v6, v2, v3
	v_add_u32_e32 v8, s57, v6
	v_and_b32_e32 v2, 0x7ff, v8
	v_add_u32_e32 v3, -1, v8
	v_cmp_ne_u32_e32 vcc, 0, v2
	v_mul_i32_i24_e32 v7, 0x140, v6
	s_nop 0
	v_cndmask_b32_e32 v9, -1, v3, vcc
	v_add_u32_e32 v3, 8, v8
	v_cmp_lt_i32_e32 vcc, s23, v8
	v_sub_u32_e32 v2, v5, v7
	s_nop 0
	v_cndmask_b32_e32 v9, v9, v3, vcc
	v_ashrrev_i32_e32 v3, 31, v2
	v_cmp_lt_i32_e32 vcc, -1, v9
	v_lshlrev_b64 v[14:15], 2, v[2:3]
	v_mov_b32_e32 v53, v2
	v_cndmask_b32_e32 v3, v8, v9, vcc
	v_mad_i64_i32 v[12:13], s[44:45], v8, s24, v[10:11]
	v_mad_i64_i32 v[8:9], s[44:45], v3, s24, v[10:11]
	v_lshl_add_u64 v[12:13], v[12:13], 0, v[14:15]
	v_lshl_add_u64 v[8:9], v[8:9], 0, v[14:15]
	global_load_dword v23, v[12:13], off
	global_load_dword v33, v[8:9], off offset:1536
	v_cndmask_b32_e64 v43, 0, 1.0, vcc
	v_mov_b32_e32 v63, v6
	v_add_u32_e32 v5, 0x200, v5
	v_mul_hi_i32 v2, v5, s22
	v_lshrrev_b32_e32 v3, 31, v2
	v_ashrrev_i32_e32 v2, 7, v2
	v_add_u32_e32 v6, v2, v3
	v_add_u32_e32 v8, s57, v6
	v_and_b32_e32 v2, 0x7ff, v8
	v_add_u32_e32 v3, -1, v8
	v_cmp_ne_u32_e32 vcc, 0, v2
	v_mul_i32_i24_e32 v7, 0x140, v6
	s_nop 0
	v_cndmask_b32_e32 v9, -1, v3, vcc
	v_add_u32_e32 v3, 8, v8
	v_cmp_lt_i32_e32 vcc, s23, v8
	v_sub_u32_e32 v2, v5, v7
	s_nop 0
	v_cndmask_b32_e32 v9, v9, v3, vcc
	v_ashrrev_i32_e32 v3, 31, v2
	v_cmp_lt_i32_e32 vcc, -1, v9
	v_lshlrev_b64 v[14:15], 2, v[2:3]
	v_mov_b32_e32 v54, v2
	v_cndmask_b32_e32 v3, v8, v9, vcc
	v_mad_i64_i32 v[12:13], s[44:45], v8, s24, v[10:11]
	v_mad_i64_i32 v[8:9], s[44:45], v3, s24, v[10:11]
	v_lshl_add_u64 v[12:13], v[12:13], 0, v[14:15]
	v_lshl_add_u64 v[8:9], v[8:9], 0, v[14:15]
	global_load_dword v24, v[12:13], off
	global_load_dword v34, v[8:9], off offset:1536
	v_cndmask_b32_e64 v44, 0, 1.0, vcc
	v_mov_b32_e32 v64, v6
	v_add_u32_e32 v5, 0x200, v5
	v_mul_hi_i32 v2, v5, s22
	v_lshrrev_b32_e32 v3, 31, v2
	v_ashrrev_i32_e32 v2, 7, v2
	v_add_u32_e32 v6, v2, v3
	v_add_u32_e32 v8, s57, v6
	v_and_b32_e32 v2, 0x7ff, v8
	v_add_u32_e32 v3, -1, v8
	v_cmp_ne_u32_e32 vcc, 0, v2
	v_mul_i32_i24_e32 v7, 0x140, v6
	s_nop 0
	v_cndmask_b32_e32 v9, -1, v3, vcc
	v_add_u32_e32 v3, 8, v8
	v_cmp_lt_i32_e32 vcc, s23, v8
	v_sub_u32_e32 v2, v5, v7
	s_nop 0
	v_cndmask_b32_e32 v9, v9, v3, vcc
	v_ashrrev_i32_e32 v3, 31, v2
	v_cmp_lt_i32_e32 vcc, -1, v9
	v_lshlrev_b64 v[14:15], 2, v[2:3]
	v_mov_b32_e32 v55, v2
	v_cndmask_b32_e32 v3, v8, v9, vcc
	v_mad_i64_i32 v[12:13], s[44:45], v8, s24, v[10:11]
	v_mad_i64_i32 v[8:9], s[44:45], v3, s24, v[10:11]
	v_lshl_add_u64 v[12:13], v[12:13], 0, v[14:15]
	v_lshl_add_u64 v[8:9], v[8:9], 0, v[14:15]
	global_load_dword v25, v[12:13], off
	global_load_dword v35, v[8:9], off offset:1536
	v_cndmask_b32_e64 v45, 0, 1.0, vcc
	v_mov_b32_e32 v65, v6
	v_add_u32_e32 v5, 0x200, v5
	v_mul_hi_i32 v2, v5, s22
	v_lshrrev_b32_e32 v3, 31, v2
	v_ashrrev_i32_e32 v2, 7, v2
	v_add_u32_e32 v6, v2, v3
	v_add_u32_e32 v8, s57, v6
	v_and_b32_e32 v2, 0x7ff, v8
	v_add_u32_e32 v3, -1, v8
	v_cmp_ne_u32_e32 vcc, 0, v2
	v_mul_i32_i24_e32 v7, 0x140, v6
	s_nop 0
	v_cndmask_b32_e32 v9, -1, v3, vcc
	v_add_u32_e32 v3, 8, v8
	v_cmp_lt_i32_e32 vcc, s23, v8
	v_sub_u32_e32 v2, v5, v7
	s_nop 0
	v_cndmask_b32_e32 v9, v9, v3, vcc
	v_ashrrev_i32_e32 v3, 31, v2
	v_cmp_lt_i32_e32 vcc, -1, v9
	v_lshlrev_b64 v[14:15], 2, v[2:3]
	v_mov_b32_e32 v56, v2
	v_cndmask_b32_e32 v3, v8, v9, vcc
	v_mad_i64_i32 v[12:13], s[44:45], v8, s24, v[10:11]
	v_mad_i64_i32 v[8:9], s[44:45], v3, s24, v[10:11]
	v_lshl_add_u64 v[12:13], v[12:13], 0, v[14:15]
	v_lshl_add_u64 v[8:9], v[8:9], 0, v[14:15]
	global_load_dword v26, v[12:13], off
	global_load_dword v36, v[8:9], off offset:1536
	v_cndmask_b32_e64 v46, 0, 1.0, vcc
	v_mov_b32_e32 v68, v6
	v_add_u32_e32 v5, 0x200, v5
	v_mul_hi_i32 v2, v5, s22
	v_lshrrev_b32_e32 v3, 31, v2
	v_ashrrev_i32_e32 v2, 7, v2
	v_add_u32_e32 v6, v2, v3
	v_add_u32_e32 v8, s57, v6
	v_and_b32_e32 v2, 0x7ff, v8
	v_add_u32_e32 v3, -1, v8
	v_cmp_ne_u32_e32 vcc, 0, v2
	v_mul_i32_i24_e32 v7, 0x140, v6
	s_nop 0
	v_cndmask_b32_e32 v9, -1, v3, vcc
	v_add_u32_e32 v3, 8, v8
	v_cmp_lt_i32_e32 vcc, s23, v8
	v_sub_u32_e32 v2, v5, v7
	s_nop 0
	v_cndmask_b32_e32 v9, v9, v3, vcc
	v_ashrrev_i32_e32 v3, 31, v2
	v_cmp_lt_i32_e32 vcc, -1, v9
	v_lshlrev_b64 v[14:15], 2, v[2:3]
	v_mov_b32_e32 v57, v2
	v_cndmask_b32_e32 v3, v8, v9, vcc
	v_mad_i64_i32 v[12:13], s[44:45], v8, s24, v[10:11]
	v_mad_i64_i32 v[8:9], s[44:45], v3, s24, v[10:11]
	v_lshl_add_u64 v[12:13], v[12:13], 0, v[14:15]
	v_lshl_add_u64 v[8:9], v[8:9], 0, v[14:15]
	global_load_dword v27, v[12:13], off
	global_load_dword v37, v[8:9], off offset:1536
	v_cndmask_b32_e64 v47, 0, 1.0, vcc
	v_mov_b32_e32 v69, v6
	v_add_u32_e32 v5, 0x200, v5
	s_waitcnt vmcnt(0)
	v_fmac_f32_e32 v18, v38, v28
	v_mul_f32_e32 v8, 0xbfb8aa3b, v18
	v_exp_f32_e32 v8, v8
	v_add_f32_e32 v2, v18, v18
	v_add_f32_e32 v8, 1.0, v8
	v_div_scale_f32 v9, s[44:45], v8, v8, 1.0
	v_rcp_f32_e32 v10, v9
	v_div_scale_f32 v11, vcc, 1.0, v8, 1.0
	v_fma_f32 v12, -v9, v10, 1.0
	v_fmac_f32_e32 v10, v12, v10
	v_mul_f32_e32 v12, v11, v10
	v_fma_f32 v13, -v9, v12, v11
	v_fmac_f32_e32 v12, v13, v10
	v_fma_f32 v9, -v9, v12, v11
	v_div_fmas_f32 v9, v9, v10, v12
	v_div_fixup_f32 v8, v9, v8, 1.0
	v_add_u32_e32 v3, 0xffffff80, v48
	v_cmp_gt_u32_e32 vcc, s25, v3
	v_mul_f32_e32 v2, 0x3fb8aa3b, v2
	v_exp_f32_e32 v2, v2
	v_cndmask_b32_e32 v8, v18, v8, vcc
	v_add_f32_e32 v2, 1.0, v2
	v_div_scale_f32 v3, s[44:45], v2, v2, 2.0
	v_rcp_f32_e32 v9, v3
	v_div_scale_f32 v10, vcc, 2.0, v2, 2.0
	v_fma_f32 v11, -v3, v9, 1.0
	v_fmac_f32_e32 v9, v11, v9
	v_mul_f32_e32 v11, v10, v9
	v_fma_f32 v12, -v3, v11, v10
	v_fmac_f32_e32 v11, v12, v9
	v_fma_f32 v3, -v3, v11, v10
	v_div_fmas_f32 v3, v3, v9, v11
	v_div_fixup_f32 v2, v3, v2, 2.0
	v_sub_f32_e32 v2, 1.0, v2
	v_cmp_lt_i32_e32 vcc, 63, v48
	v_mul_i32_i24_e32 v3, 0x290, v58
	v_lshlrev_b32_e32 v6, 1, v48
	v_cndmask_b32_e32 v8, v2, v8, vcc
	v_add3_u32 v3, 0, v3, v6
	v_bfe_u32 v2, v8, 16, 1
	v_add3_u32 v2, v8, v2, s33
	ds_write_b16_d16_hi v3, v2
	v_fmac_f32_e32 v19, v39, v29
	v_mul_f32_e32 v8, 0xbfb8aa3b, v19
	v_exp_f32_e32 v8, v8
	v_add_f32_e32 v2, v19, v19
	v_add_f32_e32 v8, 1.0, v8
	v_div_scale_f32 v9, s[44:45], v8, v8, 1.0
	v_rcp_f32_e32 v10, v9
	v_div_scale_f32 v11, vcc, 1.0, v8, 1.0
	v_fma_f32 v12, -v9, v10, 1.0
	v_fmac_f32_e32 v10, v12, v10
	v_mul_f32_e32 v12, v11, v10
	v_fma_f32 v13, -v9, v12, v11
	v_fmac_f32_e32 v12, v13, v10
	v_fma_f32 v9, -v9, v12, v11
	v_div_fmas_f32 v9, v9, v10, v12
	v_div_fixup_f32 v8, v9, v8, 1.0
	v_add_u32_e32 v3, 0xffffff80, v49
	v_cmp_gt_u32_e32 vcc, s25, v3
	v_mul_f32_e32 v2, 0x3fb8aa3b, v2
	v_exp_f32_e32 v2, v2
	v_cndmask_b32_e32 v8, v19, v8, vcc
	v_add_f32_e32 v2, 1.0, v2
	v_div_scale_f32 v3, s[44:45], v2, v2, 2.0
	v_rcp_f32_e32 v9, v3
	v_div_scale_f32 v10, vcc, 2.0, v2, 2.0
	v_fma_f32 v11, -v3, v9, 1.0
	v_fmac_f32_e32 v9, v11, v9
	v_mul_f32_e32 v11, v10, v9
	v_fma_f32 v12, -v3, v11, v10
	v_fmac_f32_e32 v11, v12, v9
	v_fma_f32 v3, -v3, v11, v10
	v_div_fmas_f32 v3, v3, v9, v11
	v_div_fixup_f32 v2, v3, v2, 2.0
	v_sub_f32_e32 v2, 1.0, v2
	v_cmp_lt_i32_e32 vcc, 63, v49
	v_mul_i32_i24_e32 v3, 0x290, v59
	v_lshlrev_b32_e32 v6, 1, v49
	v_cndmask_b32_e32 v8, v2, v8, vcc
	v_add3_u32 v3, 0, v3, v6
	v_bfe_u32 v2, v8, 16, 1
	v_add3_u32 v2, v8, v2, s33
	ds_write_b16_d16_hi v3, v2
	v_fmac_f32_e32 v20, v40, v30
	v_mul_f32_e32 v8, 0xbfb8aa3b, v20
	v_exp_f32_e32 v8, v8
	v_add_f32_e32 v2, v20, v20
	v_add_f32_e32 v8, 1.0, v8
	v_div_scale_f32 v9, s[44:45], v8, v8, 1.0
	v_rcp_f32_e32 v10, v9
	v_div_scale_f32 v11, vcc, 1.0, v8, 1.0
	v_fma_f32 v12, -v9, v10, 1.0
	v_fmac_f32_e32 v10, v12, v10
	v_mul_f32_e32 v12, v11, v10
	v_fma_f32 v13, -v9, v12, v11
	v_fmac_f32_e32 v12, v13, v10
	v_fma_f32 v9, -v9, v12, v11
	v_div_fmas_f32 v9, v9, v10, v12
	v_div_fixup_f32 v8, v9, v8, 1.0
	v_add_u32_e32 v3, 0xffffff80, v50
	v_cmp_gt_u32_e32 vcc, s25, v3
	v_mul_f32_e32 v2, 0x3fb8aa3b, v2
	v_exp_f32_e32 v2, v2
	v_cndmask_b32_e32 v8, v20, v8, vcc
	v_add_f32_e32 v2, 1.0, v2
	v_div_scale_f32 v3, s[44:45], v2, v2, 2.0
	v_rcp_f32_e32 v9, v3
	v_div_scale_f32 v10, vcc, 2.0, v2, 2.0
	v_fma_f32 v11, -v3, v9, 1.0
	v_fmac_f32_e32 v9, v11, v9
	v_mul_f32_e32 v11, v10, v9
	v_fma_f32 v12, -v3, v11, v10
	v_fmac_f32_e32 v11, v12, v9
	v_fma_f32 v3, -v3, v11, v10
	v_div_fmas_f32 v3, v3, v9, v11
	v_div_fixup_f32 v2, v3, v2, 2.0
	v_sub_f32_e32 v2, 1.0, v2
	v_cmp_lt_i32_e32 vcc, 63, v50
	v_mul_i32_i24_e32 v3, 0x290, v60
	v_lshlrev_b32_e32 v6, 1, v50
	v_cndmask_b32_e32 v8, v2, v8, vcc
	v_add3_u32 v3, 0, v3, v6
	v_bfe_u32 v2, v8, 16, 1
	v_add3_u32 v2, v8, v2, s33
	ds_write_b16_d16_hi v3, v2
	v_fmac_f32_e32 v21, v41, v31
	v_mul_f32_e32 v8, 0xbfb8aa3b, v21
	v_exp_f32_e32 v8, v8
	v_add_f32_e32 v2, v21, v21
	v_add_f32_e32 v8, 1.0, v8
	v_div_scale_f32 v9, s[44:45], v8, v8, 1.0
	v_rcp_f32_e32 v10, v9
	v_div_scale_f32 v11, vcc, 1.0, v8, 1.0
	v_fma_f32 v12, -v9, v10, 1.0
	v_fmac_f32_e32 v10, v12, v10
	v_mul_f32_e32 v12, v11, v10
	v_fma_f32 v13, -v9, v12, v11
	v_fmac_f32_e32 v12, v13, v10
	v_fma_f32 v9, -v9, v12, v11
	v_div_fmas_f32 v9, v9, v10, v12
	v_div_fixup_f32 v8, v9, v8, 1.0
	v_add_u32_e32 v3, 0xffffff80, v51
	v_cmp_gt_u32_e32 vcc, s25, v3
	v_mul_f32_e32 v2, 0x3fb8aa3b, v2
	v_exp_f32_e32 v2, v2
	v_cndmask_b32_e32 v8, v21, v8, vcc
	v_add_f32_e32 v2, 1.0, v2
	v_div_scale_f32 v3, s[44:45], v2, v2, 2.0
	v_rcp_f32_e32 v9, v3
	v_div_scale_f32 v10, vcc, 2.0, v2, 2.0
	v_fma_f32 v11, -v3, v9, 1.0
	v_fmac_f32_e32 v9, v11, v9
	v_mul_f32_e32 v11, v10, v9
	v_fma_f32 v12, -v3, v11, v10
	v_fmac_f32_e32 v11, v12, v9
	v_fma_f32 v3, -v3, v11, v10
	v_div_fmas_f32 v3, v3, v9, v11
	v_div_fixup_f32 v2, v3, v2, 2.0
	v_sub_f32_e32 v2, 1.0, v2
	v_cmp_lt_i32_e32 vcc, 63, v51
	v_mul_i32_i24_e32 v3, 0x290, v61
	v_lshlrev_b32_e32 v6, 1, v51
	v_cndmask_b32_e32 v8, v2, v8, vcc
	v_add3_u32 v3, 0, v3, v6
	v_bfe_u32 v2, v8, 16, 1
	v_add3_u32 v2, v8, v2, s33
	ds_write_b16_d16_hi v3, v2
	v_fmac_f32_e32 v22, v42, v32
	v_mul_f32_e32 v8, 0xbfb8aa3b, v22
	v_exp_f32_e32 v8, v8
	v_add_f32_e32 v2, v22, v22
	v_add_f32_e32 v8, 1.0, v8
	v_div_scale_f32 v9, s[44:45], v8, v8, 1.0
	v_rcp_f32_e32 v10, v9
	v_div_scale_f32 v11, vcc, 1.0, v8, 1.0
	v_fma_f32 v12, -v9, v10, 1.0
	v_fmac_f32_e32 v10, v12, v10
	v_mul_f32_e32 v12, v11, v10
	v_fma_f32 v13, -v9, v12, v11
	v_fmac_f32_e32 v12, v13, v10
	v_fma_f32 v9, -v9, v12, v11
	v_div_fmas_f32 v9, v9, v10, v12
	v_div_fixup_f32 v8, v9, v8, 1.0
	v_add_u32_e32 v3, 0xffffff80, v52
	v_cmp_gt_u32_e32 vcc, s25, v3
	v_mul_f32_e32 v2, 0x3fb8aa3b, v2
	v_exp_f32_e32 v2, v2
	v_cndmask_b32_e32 v8, v22, v8, vcc
	v_add_f32_e32 v2, 1.0, v2
	v_div_scale_f32 v3, s[44:45], v2, v2, 2.0
	v_rcp_f32_e32 v9, v3
	v_div_scale_f32 v10, vcc, 2.0, v2, 2.0
	v_fma_f32 v11, -v3, v9, 1.0
	v_fmac_f32_e32 v9, v11, v9
	v_mul_f32_e32 v11, v10, v9
	v_fma_f32 v12, -v3, v11, v10
	v_fmac_f32_e32 v11, v12, v9
	v_fma_f32 v3, -v3, v11, v10
	v_div_fmas_f32 v3, v3, v9, v11
	v_div_fixup_f32 v2, v3, v2, 2.0
	v_sub_f32_e32 v2, 1.0, v2
	v_cmp_lt_i32_e32 vcc, 63, v52
	v_mul_i32_i24_e32 v3, 0x290, v62
	v_lshlrev_b32_e32 v6, 1, v52
	v_cndmask_b32_e32 v8, v2, v8, vcc
	v_add3_u32 v3, 0, v3, v6
	v_bfe_u32 v2, v8, 16, 1
	v_add3_u32 v2, v8, v2, s33
	ds_write_b16_d16_hi v3, v2
	v_fmac_f32_e32 v23, v43, v33
	v_mul_f32_e32 v8, 0xbfb8aa3b, v23
	v_exp_f32_e32 v8, v8
	v_add_f32_e32 v2, v23, v23
	v_add_f32_e32 v8, 1.0, v8
	v_div_scale_f32 v9, s[44:45], v8, v8, 1.0
	v_rcp_f32_e32 v10, v9
	v_div_scale_f32 v11, vcc, 1.0, v8, 1.0
	v_fma_f32 v12, -v9, v10, 1.0
	v_fmac_f32_e32 v10, v12, v10
	v_mul_f32_e32 v12, v11, v10
	v_fma_f32 v13, -v9, v12, v11
	v_fmac_f32_e32 v12, v13, v10
	v_fma_f32 v9, -v9, v12, v11
	v_div_fmas_f32 v9, v9, v10, v12
	v_div_fixup_f32 v8, v9, v8, 1.0
	v_add_u32_e32 v3, 0xffffff80, v53
	v_cmp_gt_u32_e32 vcc, s25, v3
	v_mul_f32_e32 v2, 0x3fb8aa3b, v2
	v_exp_f32_e32 v2, v2
	v_cndmask_b32_e32 v8, v23, v8, vcc
	v_add_f32_e32 v2, 1.0, v2
	v_div_scale_f32 v3, s[44:45], v2, v2, 2.0
	v_rcp_f32_e32 v9, v3
	v_div_scale_f32 v10, vcc, 2.0, v2, 2.0
	v_fma_f32 v11, -v3, v9, 1.0
	v_fmac_f32_e32 v9, v11, v9
	v_mul_f32_e32 v11, v10, v9
	v_fma_f32 v12, -v3, v11, v10
	v_fmac_f32_e32 v11, v12, v9
	v_fma_f32 v3, -v3, v11, v10
	v_div_fmas_f32 v3, v3, v9, v11
	v_div_fixup_f32 v2, v3, v2, 2.0
	v_sub_f32_e32 v2, 1.0, v2
	v_cmp_lt_i32_e32 vcc, 63, v53
	v_mul_i32_i24_e32 v3, 0x290, v63
	v_lshlrev_b32_e32 v6, 1, v53
	v_cndmask_b32_e32 v8, v2, v8, vcc
	v_add3_u32 v3, 0, v3, v6
	v_bfe_u32 v2, v8, 16, 1
	v_add3_u32 v2, v8, v2, s33
	ds_write_b16_d16_hi v3, v2
	v_fmac_f32_e32 v24, v44, v34
	v_mul_f32_e32 v8, 0xbfb8aa3b, v24
	v_exp_f32_e32 v8, v8
	v_add_f32_e32 v2, v24, v24
	v_add_f32_e32 v8, 1.0, v8
	v_div_scale_f32 v9, s[44:45], v8, v8, 1.0
	v_rcp_f32_e32 v10, v9
	v_div_scale_f32 v11, vcc, 1.0, v8, 1.0
	v_fma_f32 v12, -v9, v10, 1.0
	v_fmac_f32_e32 v10, v12, v10
	v_mul_f32_e32 v12, v11, v10
	v_fma_f32 v13, -v9, v12, v11
	v_fmac_f32_e32 v12, v13, v10
	v_fma_f32 v9, -v9, v12, v11
	v_div_fmas_f32 v9, v9, v10, v12
	v_div_fixup_f32 v8, v9, v8, 1.0
	v_add_u32_e32 v3, 0xffffff80, v54
	v_cmp_gt_u32_e32 vcc, s25, v3
	v_mul_f32_e32 v2, 0x3fb8aa3b, v2
	v_exp_f32_e32 v2, v2
	v_cndmask_b32_e32 v8, v24, v8, vcc
	v_add_f32_e32 v2, 1.0, v2
	v_div_scale_f32 v3, s[44:45], v2, v2, 2.0
	v_rcp_f32_e32 v9, v3
	v_div_scale_f32 v10, vcc, 2.0, v2, 2.0
	v_fma_f32 v11, -v3, v9, 1.0
	v_fmac_f32_e32 v9, v11, v9
	v_mul_f32_e32 v11, v10, v9
	v_fma_f32 v12, -v3, v11, v10
	v_fmac_f32_e32 v11, v12, v9
	v_fma_f32 v3, -v3, v11, v10
	v_div_fmas_f32 v3, v3, v9, v11
	v_div_fixup_f32 v2, v3, v2, 2.0
	v_sub_f32_e32 v2, 1.0, v2
	v_cmp_lt_i32_e32 vcc, 63, v54
	v_mul_i32_i24_e32 v3, 0x290, v64
	v_lshlrev_b32_e32 v6, 1, v54
	v_cndmask_b32_e32 v8, v2, v8, vcc
	v_add3_u32 v3, 0, v3, v6
	v_bfe_u32 v2, v8, 16, 1
	v_add3_u32 v2, v8, v2, s33
	ds_write_b16_d16_hi v3, v2
	v_fmac_f32_e32 v25, v45, v35
	v_mul_f32_e32 v8, 0xbfb8aa3b, v25
	v_exp_f32_e32 v8, v8
	v_add_f32_e32 v2, v25, v25
	v_add_f32_e32 v8, 1.0, v8
	v_div_scale_f32 v9, s[44:45], v8, v8, 1.0
	v_rcp_f32_e32 v10, v9
	v_div_scale_f32 v11, vcc, 1.0, v8, 1.0
	v_fma_f32 v12, -v9, v10, 1.0
	v_fmac_f32_e32 v10, v12, v10
	v_mul_f32_e32 v12, v11, v10
	v_fma_f32 v13, -v9, v12, v11
	v_fmac_f32_e32 v12, v13, v10
	v_fma_f32 v9, -v9, v12, v11
	v_div_fmas_f32 v9, v9, v10, v12
	v_div_fixup_f32 v8, v9, v8, 1.0
	v_add_u32_e32 v3, 0xffffff80, v55
	v_cmp_gt_u32_e32 vcc, s25, v3
	v_mul_f32_e32 v2, 0x3fb8aa3b, v2
	v_exp_f32_e32 v2, v2
	v_cndmask_b32_e32 v8, v25, v8, vcc
	v_add_f32_e32 v2, 1.0, v2
	v_div_scale_f32 v3, s[44:45], v2, v2, 2.0
	v_rcp_f32_e32 v9, v3
	v_div_scale_f32 v10, vcc, 2.0, v2, 2.0
	v_fma_f32 v11, -v3, v9, 1.0
	v_fmac_f32_e32 v9, v11, v9
	v_mul_f32_e32 v11, v10, v9
	v_fma_f32 v12, -v3, v11, v10
	v_fmac_f32_e32 v11, v12, v9
	v_fma_f32 v3, -v3, v11, v10
	v_div_fmas_f32 v3, v3, v9, v11
	v_div_fixup_f32 v2, v3, v2, 2.0
	v_sub_f32_e32 v2, 1.0, v2
	v_cmp_lt_i32_e32 vcc, 63, v55
	v_mul_i32_i24_e32 v3, 0x290, v65
	v_lshlrev_b32_e32 v6, 1, v55
	v_cndmask_b32_e32 v8, v2, v8, vcc
	v_add3_u32 v3, 0, v3, v6
	v_bfe_u32 v2, v8, 16, 1
	v_add3_u32 v2, v8, v2, s33
	ds_write_b16_d16_hi v3, v2
	v_fmac_f32_e32 v26, v46, v36
	v_mul_f32_e32 v8, 0xbfb8aa3b, v26
	v_exp_f32_e32 v8, v8
	v_add_f32_e32 v2, v26, v26
	v_add_f32_e32 v8, 1.0, v8
	v_div_scale_f32 v9, s[44:45], v8, v8, 1.0
	v_rcp_f32_e32 v10, v9
	v_div_scale_f32 v11, vcc, 1.0, v8, 1.0
	v_fma_f32 v12, -v9, v10, 1.0
	v_fmac_f32_e32 v10, v12, v10
	v_mul_f32_e32 v12, v11, v10
	v_fma_f32 v13, -v9, v12, v11
	v_fmac_f32_e32 v12, v13, v10
	v_fma_f32 v9, -v9, v12, v11
	v_div_fmas_f32 v9, v9, v10, v12
	v_div_fixup_f32 v8, v9, v8, 1.0
	v_add_u32_e32 v3, 0xffffff80, v56
	v_cmp_gt_u32_e32 vcc, s25, v3
	v_mul_f32_e32 v2, 0x3fb8aa3b, v2
	v_exp_f32_e32 v2, v2
	v_cndmask_b32_e32 v8, v26, v8, vcc
	v_add_f32_e32 v2, 1.0, v2
	v_div_scale_f32 v3, s[44:45], v2, v2, 2.0
	v_rcp_f32_e32 v9, v3
	v_div_scale_f32 v10, vcc, 2.0, v2, 2.0
	v_fma_f32 v11, -v3, v9, 1.0
	v_fmac_f32_e32 v9, v11, v9
	v_mul_f32_e32 v11, v10, v9
	v_fma_f32 v12, -v3, v11, v10
	v_fmac_f32_e32 v11, v12, v9
	v_fma_f32 v3, -v3, v11, v10
	v_div_fmas_f32 v3, v3, v9, v11
	v_div_fixup_f32 v2, v3, v2, 2.0
	v_sub_f32_e32 v2, 1.0, v2
	v_cmp_lt_i32_e32 vcc, 63, v56
	v_mul_i32_i24_e32 v3, 0x290, v68
	v_lshlrev_b32_e32 v6, 1, v56
	v_cndmask_b32_e32 v8, v2, v8, vcc
	v_add3_u32 v3, 0, v3, v6
	v_bfe_u32 v2, v8, 16, 1
	v_add3_u32 v2, v8, v2, s33
	ds_write_b16_d16_hi v3, v2
	v_fmac_f32_e32 v27, v47, v37
	v_mul_f32_e32 v8, 0xbfb8aa3b, v27
	v_exp_f32_e32 v8, v8
	v_add_f32_e32 v2, v27, v27
	v_add_f32_e32 v8, 1.0, v8
	v_div_scale_f32 v9, s[44:45], v8, v8, 1.0
	v_rcp_f32_e32 v10, v9
	v_div_scale_f32 v11, vcc, 1.0, v8, 1.0
	v_fma_f32 v12, -v9, v10, 1.0
	v_fmac_f32_e32 v10, v12, v10
	v_mul_f32_e32 v12, v11, v10
	v_fma_f32 v13, -v9, v12, v11
	v_fmac_f32_e32 v12, v13, v10
	v_fma_f32 v9, -v9, v12, v11
	v_div_fmas_f32 v9, v9, v10, v12
	v_div_fixup_f32 v8, v9, v8, 1.0
	v_add_u32_e32 v3, 0xffffff80, v57
	v_cmp_gt_u32_e32 vcc, s25, v3
	v_mul_f32_e32 v2, 0x3fb8aa3b, v2
	v_exp_f32_e32 v2, v2
	v_cndmask_b32_e32 v8, v27, v8, vcc
	v_add_f32_e32 v2, 1.0, v2
	v_div_scale_f32 v3, s[44:45], v2, v2, 2.0
	v_rcp_f32_e32 v9, v3
	v_div_scale_f32 v10, vcc, 2.0, v2, 2.0
	v_fma_f32 v11, -v3, v9, 1.0
	v_fmac_f32_e32 v9, v11, v9
	v_mul_f32_e32 v11, v10, v9
	v_fma_f32 v12, -v3, v11, v10
	v_fmac_f32_e32 v11, v12, v9
	v_fma_f32 v3, -v3, v11, v10
	v_div_fmas_f32 v3, v3, v9, v11
	v_div_fixup_f32 v2, v3, v2, 2.0
	v_sub_f32_e32 v2, 1.0, v2
	v_cmp_lt_i32_e32 vcc, 63, v57
	v_mul_i32_i24_e32 v3, 0x290, v69
	v_lshlrev_b32_e32 v6, 1, v57
	v_cndmask_b32_e32 v8, v2, v8, vcc
	v_add3_u32 v3, 0, v3, v6
	v_bfe_u32 v2, v8, 16, 1
	v_add3_u32 v2, v8, v2, s33
	ds_write_b16_d16_hi v3, v2
	v_cmp_le_i32_e32 vcc, s28, v5
	s_or_b64 s[0:1], vcc, s[0:1]
	s_andn2_b64 exec, exec, s[0:1]
	s_cbranch_execnz .LBB0_537
